# speedup vs baseline: 1.0111x; 1.0111x over previous
; __device__ __forceinline__ void phase_branch(const KP2& p, int l, LAS unsigned char* lds) {
;     ...
;     for (int u = blockIdx.x; u < 256 + 5 * NBS; u += gridDim.x) {
.LBB0_369:
	s_add_i32 s87, s87, s24
	s_cmpk_lt_i32 s87, 0x1e0
	s_cbranch_scc0 .LBB0_536

; __device__ __forceinline__ void phase_branch(const KP2& p, int l, LAS unsigned char* lds) {
;     ...
;     for (int u = blockIdx.x; u < 256 + 5 * NBS; u += gridDim.x) {
;         const bool smp = u >= 256;
;         int b, t0, row0, R, um, h0 = 0, h1 = 4;
;         if (!smp) { b = u >> 4; t0 = (u & 15) * 128; row0 = b * SEQ + t0; R = 128; um = 15; }
;         else { const int q = u - 256, part = q % 5; b = q / 5; t0 = 0; row0 = MP + b * SSEQ; R = 32; um = part < 3 ? (1 << part) : 8; if (part == 3) h1 = 2; if (part == 4) h0 = 2; }
;         const bool last = smp || (u & 15) == 15;
;         const int i0 = wave * 16;
;         const bool wact = i0 < R;
;         if ((BR_MASK & 1) && (um & 1)) {
.LBB0_372:
	s_andn2_b64 vcc, exec, s[8:9]
	s_cbranch_vccnz .LBB0_374
	s_and_b32 s4, s87, 0xff
	s_mulk_i32 s4, 0x125
	s_lshr_b32 s72, s4, 11
	s_mul_i32 s4, s72, 7
	s_sub_i32 s4, s87, s4
	s_lshl_b32 s5, s72, 5
	s_and_b32 s8, s4, 0xff
	s_bitset1_b32 s5, 15
	s_lshl_b32 s4, 1, s4
	s_cmp_lt_u32 s8, 3
	s_cselect_b32 s86, s4, 8
	s_sub_i32 s4, s8, 3
	s_max_i32 s4, s4, 0
	s_add_i32 s89, s4, 1
	s_mov_b32 s43, 0
	s_mov_b32 s54, 32
	s_movk_i32 s42, 0x801
	s_bitcmp0_b32 s86, 0
	v_cmp_gt_i32_e64 s[8:9], s54, v215
	s_cbranch_scc0 .LBB0_375
	s_branch .LBB0_418
